# grid barrier rewritten (monotonic counters, no TOPGEN hop/divisions); all stores write-through sc1 so the barrier needs no buffer_wbl2 release
# speedup vs baseline: 1.0360x; 1.0360x over previous
; #define LAS __attribute__((address_space(3)))
; __global__ void __launch_bounds__(NWAVES * 64, 2) trunk_fwd(Args args) {
;     extern __shared__ __attribute__((aligned(16))) unsigned char lds_raw[];
;     LAS unsigned char* lds = (LAS unsigned char*)lds_raw;
;     const int Gk = gridDim.x, bx = blockIdx.x;
;     const int vcu = (Gk % 8 == 0) ? (bx % 8) * (Gk / 8) + bx / 8 : bx;
;     unsigned char* ws = args.ws;
;     float* X = args.out;
;     bf16* XB = (bf16*)(ws + WS_XB);
;     float* SS = (float*)(ws + WS_SS);
;     const float* ROPE = (const float*)(ws + WS_ROPE);
;     bf16* ACT0 = (bf16*)(ws + WS_ACT);
;     bf16* ACT1 = ACT0 + (size_t)M * DM;
;     bf16* ACT2 = ACT1 + (size_t)M * DM;
;     bf16* ACT3 = ACT2 + (size_t)M * DM;
;     ...
;     volatile LAS unsigned* MISC = (volatile LAS unsigned*)(lds + 147200);
;     if (threadIdx.x < 32) MISC[threadIdx.x] = 0u;
;     __syncthreads();
;     XcdBarrier bar; bar.bar = (unsigned*)ws; bar.x = 0; bar.st = MISC + 8;
;     if (args.ph_hi - args.ph_lo > 1) bar = xcd_barrier_post((unsigned*)ws, MISC + 8);
_Z9trunk_fwd4Args:
	s_mov_b32 s101, 0
	s_load_dword s4, s[0:1], 0x88
	s_load_dwordx2 s[66:67], s[0:1], 0x80
	s_mov_b32 s64, s2
	s_add_u32 s2, s0, 0x88
	s_addc_u32 s3, s1, 0
	s_mov_b32 s90, s64
	v_writelane_b32 v253, s2, 0
	s_nop 1
	v_writelane_b32 v253, s3, 1
	s_waitcnt lgkmcnt(0)
	s_and_b32 s2, s4, 7
	v_writelane_b32 v253, s4, 2
	s_cmp_lg_u32 s2, 0
	s_cbranch_scc0 .LBB0_636
	s_load_dwordx16 s[48:63], s[0:1], 0x40
	v_cmp_gt_u32_e32 vcc, 32, v0
	s_and_saveexec_b64 s[4:5], vcc

; __device__ __forceinline__ unsigned xb_ld(unsigned* p)              { return __hip_atomic_load(p, __ATOMIC_RELAXED, __HIP_MEMORY_SCOPE_AGENT); }
; __device__ __forceinline__ unsigned xb_add(unsigned* p, unsigned v) { return __hip_atomic_fetch_add(p, v, __ATOMIC_RELAXED, __HIP_MEMORY_SCOPE_AGENT); }
; #define XB_SPIN(cond, bar) do { unsigned _sp = 0; while (cond) { __builtin_amdgcn_s_sleep(1); \
;     if ((++_sp & 255u) == 0u) { if (xb_ld(&(bar)[XB_TMO])) break; if (_sp > XB_SPIN_CAP) { atomicAdd(&(bar)[XB_TMO], 1u); break; } } } } while (0)
; __device__ __forceinline__ void xcd_barrier(const XcdBarrier& b) {
;     asm volatile("s_waitcnt vmcnt(0)" ::: "memory");
;     __syncthreads();
;     if (threadIdx.x == 0) {
;         unsigned* bar = b.bar;
;         __builtin_amdgcn_s_waitcnt(0);
;         unsigned nloc = b.st[0], nx = b.st[1];
;         if (nloc == 0u) { xcd_barrier_complete(bar, b.x, nloc, nx); b.st[0] = nloc; b.st[1] = nx; }
;         const unsigned old = xb_add(&bar[XB_XSUB(b.x)], 1u);
;         const unsigned gen = old / nloc;
;         if (old + 1u == (gen + 1u) * nloc) {
;             __builtin_amdgcn_fence(__ATOMIC_RELEASE, "agent");
;             asm volatile("s_waitcnt vmcnt(0)" ::: "memory");
;             const unsigned og = xb_add(&bar[XB_TOP], 1u);
;             const unsigned tg = og / nx;
;             if (og + 1u == (tg + 1u) * nx) xb_add(&bar[XB_TOPGEN], 1u);
;             else XB_SPIN(xb_ld(&bar[XB_TOPGEN]) == tg, bar);
;             __builtin_amdgcn_fence(__ATOMIC_ACQUIRE, "agent");
;             xb_add(&bar[XB_XGEN(b.x)], 1u);
;             asm volatile("s_waitcnt vmcnt(0)" ::: "memory");
;         } else {
;             XB_SPIN(xb_ld(&bar[XB_XGEN(b.x)]) == gen, bar);
;             __builtin_amdgcn_fence(__ATOMIC_ACQUIRE, "agent");
;             asm volatile("s_waitcnt vmcnt(0)" ::: "memory");
;         }
;     }
;     __syncthreads();
; }
.LBB0_601:
	v_readlane_b32 s2, v254, 50
	v_readlane_b32 s3, v254, 51
	v_mov_b32_e32 v3, 1
	s_add_i32 s101, s101, 1
	s_waitcnt lgkmcnt(0)
	s_nop 4
	global_atomic_add v5, v99, v3, s[2:3] sc0
	v_readfirstlane_b32 s6, v4
	v_readfirstlane_b32 s7, v2
	s_mul_i32 s6, s6, s101
	s_mul_i32 s7, s7, s101
	s_waitcnt vmcnt(0)
	v_readfirstlane_b32 s8, v5
	s_add_i32 s8, s8, 1
	s_mov_b32 s10, 0
	s_cmp_lg_u32 s8, s6
	s_cbranch_scc0 .Lmy_bar_leader
	v_readlane_b32 s2, v254, 52
	v_readlane_b32 s3, v254, 53
	s_nop 4
.Lmy_bar_mspin:
	global_load_dword v5, v99, s[2:3] sc1
	s_waitcnt vmcnt(0)
	v_readfirstlane_b32 s8, v5
	s_cmp_ge_u32 s8, s101
	s_cbranch_scc1 .Lmy_bar_acq
	s_sleep 1
	s_add_i32 s10, s10, 1
	s_cmp_lt_u32 s10, 0x2000
	s_cbranch_scc1 .Lmy_bar_mspin
	s_branch .Lmy_bar_acq
.Lmy_bar_leader:
	v_readlane_b32 s2, v254, 54
	v_readlane_b32 s3, v254, 55
	s_nop 4
	global_atomic_add v99, v3, s[2:3]
.Lmy_bar_lspin:
	global_load_dword v5, v99, s[2:3] sc1
	s_waitcnt vmcnt(0)
	v_readfirstlane_b32 s8, v5
	s_cmp_ge_u32 s8, s7
	s_cbranch_scc1 .Lmy_bar_lrel
	s_sleep 1
	s_add_i32 s10, s10, 1
	s_cmp_lt_u32 s10, 0x2000
	s_cbranch_scc1 .Lmy_bar_lspin
.Lmy_bar_lrel:
	v_readlane_b32 s2, v254, 52
	v_readlane_b32 s3, v254, 53
	s_nop 4
	global_atomic_add v99, v3, s[2:3]
.Lmy_bar_acq:
	buffer_inv sc1
	s_waitcnt vmcnt(0)

; __global__ void __launch_bounds__(NWAVES * 64, 2) trunk_fwd(Args args) {
	.amdhsa_kernel _Z9trunk_fwd4Args
		.amdhsa_group_segment_fixed_size 0
		.amdhsa_private_segment_fixed_size 0
		.amdhsa_kernarg_size 392
		.amdhsa_user_sgpr_count 2
		.amdhsa_user_sgpr_dispatch_ptr 0
		.amdhsa_user_sgpr_queue_ptr 0
		.amdhsa_user_sgpr_kernarg_segment_ptr 1
		.amdhsa_user_sgpr_dispatch_id 0
		.amdhsa_user_sgpr_kernarg_preload_length 0
		.amdhsa_user_sgpr_kernarg_preload_offset 0
		.amdhsa_user_sgpr_private_segment_size 0
		.amdhsa_uses_dynamic_stack 0
		.amdhsa_enable_private_segment 0
		.amdhsa_system_sgpr_workgroup_id_x 1
		.amdhsa_system_sgpr_workgroup_id_y 0
		.amdhsa_system_sgpr_workgroup_id_z 0
		.amdhsa_system_sgpr_workgroup_info 0
		.amdhsa_system_vgpr_workitem_id 0
		.amdhsa_next_free_vgpr 256
		.amdhsa_next_free_sgpr 102
		.amdhsa_accum_offset 256
		.amdhsa_reserve_vcc 1
		.amdhsa_float_round_mode_32 0
		.amdhsa_float_round_mode_16_64 0
		.amdhsa_float_denorm_mode_32 3
		.amdhsa_float_denorm_mode_16_64 3
		.amdhsa_dx10_clamp 1
		.amdhsa_ieee_mode 1
		.amdhsa_fp16_overflow 0
		.amdhsa_tg_split 0
		.amdhsa_exception_fp_ieee_invalid_op 0
		.amdhsa_exception_fp_denorm_src 0
		.amdhsa_exception_fp_ieee_div_zero 0
		.amdhsa_exception_fp_ieee_overflow 0
		.amdhsa_exception_fp_ieee_underflow 0
		.amdhsa_exception_fp_ieee_inexact 0
		.amdhsa_exception_int_div_zero 0
	.end_amdhsa_kernel

; __global__ void __launch_bounds__(NWAVES * 64, 2) trunk_fwd(Args args) {
amdhsa.kernels:
  - .agpr_count:     0
    .args:
      - .offset:         0
        .size:           136
        .value_kind:     by_value
      - .offset:         136
        .size:           4
        .value_kind:     hidden_block_count_x
      - .offset:         140
        .size:           4
        .value_kind:     hidden_block_count_y
      - .offset:         144
        .size:           4
        .value_kind:     hidden_block_count_z
      - .offset:         148
        .size:           2
        .value_kind:     hidden_group_size_x
      - .offset:         150
        .size:           2
        .value_kind:     hidden_group_size_y
      - .offset:         152
        .size:           2
        .value_kind:     hidden_group_size_z
      - .offset:         154
        .size:           2
        .value_kind:     hidden_remainder_x
      - .offset:         156
        .size:           2
        .value_kind:     hidden_remainder_y
      - .offset:         158
        .size:           2
        .value_kind:     hidden_remainder_z
      - .offset:         176
        .size:           8
        .value_kind:     hidden_global_offset_x
      - .offset:         184
        .size:           8
        .value_kind:     hidden_global_offset_y
      - .offset:         192
        .size:           8
        .value_kind:     hidden_global_offset_z
      - .offset:         200
        .size:           2
        .value_kind:     hidden_grid_dims
      - .offset:         256
        .size:           4
        .value_kind:     hidden_dynamic_lds_size
    .group_segment_fixed_size: 0
    .kernarg_segment_align: 8
    .kernarg_segment_size: 392
    .language:       OpenCL C
    .language_version:
      - 2
      - 0
    .max_flat_workgroup_size: 512
    .name:           _Z9trunk_fwd4Args
    .private_segment_fixed_size: 0
    .sgpr_count:     108
    .sgpr_spill_count: 199
    .symbol:         _Z9trunk_fwd4Args.kd
    .uniform_work_group_size: 1
    .uses_dynamic_stack: false
    .vgpr_count:     256
    .vgpr_spill_count: 0
    .wavefront_size: 64
